# v19: v16 with the hand-written P4 epilogue using plain v_mul_f32 squares (packed f32 multiplies measured slower in v18) and SGPR-base + 32-bit offset stores
# speedup vs baseline: 1.0078x; 1.0078x over previous
; #define PG8_STAGE(bufoff, gbase, voff) do { _Pragma("unroll") for (int _i = 0; _i < 2; ++_i) \
;         __builtin_amdgcn_global_load_lds((const unsigned*)((const char*)(gbase) + (voff)[_i]), (LAS unsigned*)(lds + (bufoff) + ldsw + _i * 8192), 16, 0, 0); } while (0)
; #define PG8_LDA(dst, b, h) do { _Pragma("unroll") for (int m = 0; m < 4; ++m) _Pragma("unroll") for (int k = 0; k < 2; ++k) dst[m][k] = *(const LAS bf16x8*)(lds + PG8_SA(b, h) + aoff + m * 2048 + k * 1024); } while (0)
; #define PG8_LDB(dst, b, h) do { _Pragma("unroll") for (int n = 0; n < 2; ++n) _Pragma("unroll") for (int k = 0; k < 2; ++k) dst[n][k] = *(const LAS bf16x8*)(lds + PG8_SB(b, h) + boff + n * 2048 + k * 1024); } while (0)
; #define PG8_MMA(ai, bj, At, Bt) do { __builtin_amdgcn_s_setprio(1); _Pragma("unroll") for (int m = 0; m < 4; ++m) _Pragma("unroll") for (int n = 0; n < 2; ++n) _Pragma("unroll") for (int k = 0; k < 2; ++k) \
;         acc[ai][bj][m][n] = __builtin_amdgcn_mfma_f32_16x16x32_bf16(Bt[n][k], At[m][k], acc[ai][bj][m][n], 0, 0, 0); __builtin_amdgcn_s_setprio(0); } while (0)
; #define PG8_WAIT_V(n) asm volatile("s_waitcnt vmcnt(" #n ")" ::: "memory")
; #define PG8_WAIT_L(n) asm volatile("s_waitcnt lgkmcnt(" #n ")" ::: "memory")
; #define PG8_BAR __builtin_amdgcn_s_barrier()
; #define PG8_SCHED __builtin_amdgcn_sched_barrier(0)
; template <class Epi, class Ptrs>
; __device__ __forceinline__ void gemm_phase(LAS unsigned char* lds, const int K, const StaticOrder& S, const Ptrs& P, const Epi& E) {
;     ...
;             const char* a1 = cA + (size_t)(t + 1) * kstep;
;             const char* a2 = last ? nA : cA + (size_t)(t + 2) * kstep; const char* b2 = last ? nB : cB + (size_t)(t + 2) * kstep;
;             const char* a3 = a2 + kstep; const char* b3 = b2 + kstep;
;             PG8_LDB(B0, 0, 0); PG8_SCHED; PG8_LDA(At, 0, 0); PG8_STAGE(PG8_SA(1, 1), a1 + hstep, voffA);
;             PG8_WAIT_L(8); PG8_BAR; PG8_WAIT_L(0); PG8_MMA(0, 0, At, B0); PG8_BAR; PG8_SCHED;
;             PG8_LDB(B1, 0, 1); PG8_STAGE(PG8_SB(0, 0), b2, voffB);
;             PG8_BAR; PG8_WAIT_L(0); PG8_MMA(0, 1, At, B1); PG8_BAR;
;             PG8_LDA(At, 0, 1); PG8_STAGE(PG8_SA(0, 0), a2, voffA);
;             PG8_BAR; PG8_WAIT_L(0); PG8_MMA(1, 0, At, B0); PG8_BAR; PG8_SCHED;
;             PG8_STAGE(PG8_SB(0, 1), b2 + hstep, voffB);
;             PG8_WAIT_V(6); PG8_BAR; PG8_MMA(1, 1, At, B1); PG8_BAR;
.LBB0_433:
	ds_read_b128 v[152:155], v149
	ds_read_b128 v[156:159], v149 offset:1024
	ds_read_b128 v[160:163], v149 offset:2048
	ds_read_b128 v[164:167], v149 offset:3072
	s_add_u32 s42, s40, 0xfffc0080
	s_addc_u32 s43, s41, -1
	s_cmp_eq_u32 s70, 12
	s_cselect_b32 s45, s1, s43
	s_cselect_b32 s44, s0, s42
	s_cselect_b32 s43, s37, s25
	s_cselect_b32 s42, s36, s23
	s_add_i32 m0, s39, 0xc000
	ds_read_b128 v[168:171], v150
	ds_read_b128 v[172:175], v150 offset:1024
	ds_read_b128 v[176:179], v150 offset:2048
	ds_read_b128 v[180:183], v150 offset:3072
	ds_read_b128 v[184:187], v150 offset:4096
	ds_read_b128 v[188:191], v150 offset:5120
	ds_read_b128 v[192:195], v150 offset:6144
	ds_read_b128 v[196:199], v150 offset:7168
	global_load_lds_dwordx4 v136, s[40:41]
	s_add_i32 m0, s39, 0xe000
	s_nop 0
	global_load_lds_dwordx4 v138, s[40:41]
	s_waitcnt lgkmcnt(8)
	s_barrier
	s_waitcnt lgkmcnt(0)
	v_mfma_f32_16x16x32_bf16 v[124:127], v[152:155], v[168:171], v[124:127]
	v_mfma_f32_16x16x32_bf16 v[124:127], v[156:159], v[172:175], v[124:127]
	v_mfma_f32_16x16x32_bf16 v[120:123], v[164:167], v[172:175], v[120:123]
	v_mfma_f32_16x16x32_bf16 v[120:123], v[160:163], v[168:171], v[120:123]
	v_mfma_f32_16x16x32_bf16 v[104:107], v[160:163], v[176:179], v[104:107]
	v_mfma_f32_16x16x32_bf16 v[104:107], v[164:167], v[180:183], v[104:107]
	v_mfma_f32_16x16x32_bf16 v[108:111], v[156:159], v[180:183], v[108:111]
	v_mfma_f32_16x16x32_bf16 v[108:111], v[152:155], v[176:179], v[108:111]
	v_mfma_f32_16x16x32_bf16 v[92:95], v[152:155], v[184:187], v[92:95]
	v_mfma_f32_16x16x32_bf16 v[92:95], v[156:159], v[188:191], v[92:95]
	v_mfma_f32_16x16x32_bf16 v[88:91], v[164:167], v[188:191], v[88:91]
	v_mfma_f32_16x16x32_bf16 v[88:91], v[160:163], v[184:187], v[88:91]
	v_mfma_f32_16x16x32_bf16 v[72:75], v[160:163], v[192:195], v[72:75]
	v_mfma_f32_16x16x32_bf16 v[72:75], v[164:167], v[196:199], v[72:75]
	v_mfma_f32_16x16x32_bf16 v[76:79], v[156:159], v[196:199], v[76:79]
	v_mfma_f32_16x16x32_bf16 v[76:79], v[152:155], v[192:195], v[76:79]
	s_barrier
	s_add_i32 s71, s63, s51
	s_add_u32 s76, s42, 0x80
	s_addc_u32 s77, s43, 0
	s_mov_b32 m0, s71
	ds_read_b128 v[200:203], v151
	ds_read_b128 v[204:207], v151 offset:1024
	ds_read_b128 v[210:213], v151 offset:2048
	ds_read_b128 v[214:217], v151 offset:3072
	global_load_lds_dwordx4 v130, s[42:43]
	s_add_i32 m0, s71, 0x2000
	s_nop 0
	global_load_lds_dwordx4 v134, s[42:43]
	s_barrier
	s_waitcnt lgkmcnt(0)
	v_mfma_f32_16x16x32_bf16 v[116:119], v[200:203], v[168:171], v[116:119]
	v_mfma_f32_16x16x32_bf16 v[116:119], v[204:207], v[172:175], v[116:119]
	v_mfma_f32_16x16x32_bf16 v[112:115], v[214:217], v[172:175], v[112:115]
	v_mfma_f32_16x16x32_bf16 v[112:115], v[210:213], v[168:171], v[112:115]
	v_mfma_f32_16x16x32_bf16 v[96:99], v[210:213], v[176:179], v[96:99]
	v_mfma_f32_16x16x32_bf16 v[96:99], v[214:217], v[180:183], v[96:99]
	v_mfma_f32_16x16x32_bf16 v[100:103], v[204:207], v[180:183], v[100:103]
	v_mfma_f32_16x16x32_bf16 v[100:103], v[200:203], v[176:179], v[100:103]
	v_mfma_f32_16x16x32_bf16 v[84:87], v[200:203], v[184:187], v[84:87]
	v_mfma_f32_16x16x32_bf16 v[84:87], v[204:207], v[188:191], v[84:87]
	v_mfma_f32_16x16x32_bf16 v[80:83], v[214:217], v[188:191], v[80:83]
	v_mfma_f32_16x16x32_bf16 v[80:83], v[210:213], v[184:187], v[80:83]
	v_mfma_f32_16x16x32_bf16 v[64:67], v[210:213], v[192:195], v[64:67]
	v_mfma_f32_16x16x32_bf16 v[64:67], v[214:217], v[196:199], v[64:67]
	v_mfma_f32_16x16x32_bf16 v[68:71], v[204:207], v[196:199], v[68:71]
	v_mfma_f32_16x16x32_bf16 v[68:71], v[200:203], v[192:195], v[68:71]
	s_barrier
	s_mov_b32 m0, s39
	s_add_u32 s78, s44, 0x80
	s_addc_u32 s79, s45, 0
	ds_read_b128 v[168:171], v150 offset:16384
	ds_read_b128 v[172:175], v150 offset:17408
	ds_read_b128 v[176:179], v150 offset:18432
	ds_read_b128 v[180:183], v150 offset:19456
	ds_read_b128 v[184:187], v150 offset:20480
	ds_read_b128 v[188:191], v150 offset:21504
	ds_read_b128 v[192:195], v150 offset:22528
	ds_read_b128 v[196:199], v150 offset:23552
	global_load_lds_dwordx4 v128, s[44:45]
	s_mov_b32 m0, s56
	s_nop 0
	global_load_lds_dwordx4 v132, s[44:45]
	s_barrier
	s_waitcnt lgkmcnt(0)
	v_mfma_f32_16x16x32_bf16 v[60:63], v[152:155], v[168:171], v[60:63]
	v_mfma_f32_16x16x32_bf16 v[60:63], v[156:159], v[172:175], v[60:63]
	v_mfma_f32_16x16x32_bf16 v[56:59], v[164:167], v[172:175], v[56:59]
	v_mfma_f32_16x16x32_bf16 v[56:59], v[160:163], v[168:171], v[56:59]
	v_mfma_f32_16x16x32_bf16 v[40:43], v[160:163], v[176:179], v[40:43]
	v_mfma_f32_16x16x32_bf16 v[40:43], v[164:167], v[180:183], v[40:43]
	v_mfma_f32_16x16x32_bf16 v[44:47], v[156:159], v[180:183], v[44:47]
	v_mfma_f32_16x16x32_bf16 v[44:47], v[152:155], v[176:179], v[44:47]
	v_mfma_f32_16x16x32_bf16 v[28:31], v[152:155], v[184:187], v[28:31]
	v_mfma_f32_16x16x32_bf16 v[28:31], v[156:159], v[188:191], v[28:31]
	v_mfma_f32_16x16x32_bf16 v[24:27], v[164:167], v[188:191], v[24:27]
	v_mfma_f32_16x16x32_bf16 v[24:27], v[160:163], v[184:187], v[24:27]
	v_mfma_f32_16x16x32_bf16 v[8:11], v[160:163], v[192:195], v[8:11]
	v_mfma_f32_16x16x32_bf16 v[8:11], v[164:167], v[196:199], v[8:11]
	v_mfma_f32_16x16x32_bf16 v[12:15], v[156:159], v[196:199], v[12:15]
	v_mfma_f32_16x16x32_bf16 v[12:15], v[152:155], v[192:195], v[12:15]
	s_barrier
	s_add_u32 s72, s42, 0x40000
	s_addc_u32 s73, s43, 0
	s_add_i32 s71, s64, s51
	s_mov_b32 m0, s71
	s_nop 0
	global_load_lds_dwordx4 v130, s[72:73]
	s_add_i32 m0, s71, 0x2000
	s_nop 0
	global_load_lds_dwordx4 v134, s[72:73]
	s_waitcnt vmcnt(6)
	s_barrier
; #define PG8_STAGE(bufoff, gbase, voff) do { _Pragma("unroll") for (int _i = 0; _i < 2; ++_i) \
;         __builtin_amdgcn_global_load_lds((const unsigned*)((const char*)(gbase) + (voff)[_i]), (LAS unsigned*)(lds + (bufoff) + ldsw + _i * 8192), 16, 0, 0); } while (0)
; #define PG8_LDA(dst, b, h) do { _Pragma("unroll") for (int m = 0; m < 4; ++m) _Pragma("unroll") for (int k = 0; k < 2; ++k) dst[m][k] = *(const LAS bf16x8*)(lds + PG8_SA(b, h) + aoff + m * 2048 + k * 1024); } while (0)
; #define PG8_LDB(dst, b, h) do { _Pragma("unroll") for (int n = 0; n < 2; ++n) _Pragma("unroll") for (int k = 0; k < 2; ++k) dst[n][k] = *(const LAS bf16x8*)(lds + PG8_SB(b, h) + boff + n * 2048 + k * 1024); } while (0)
; #define PG8_MMA(ai, bj, At, Bt) do { __builtin_amdgcn_s_setprio(1); _Pragma("unroll") for (int m = 0; m < 4; ++m) _Pragma("unroll") for (int n = 0; n < 2; ++n) _Pragma("unroll") for (int k = 0; k < 2; ++k) \
;         acc[ai][bj][m][n] = __builtin_amdgcn_mfma_f32_16x16x32_bf16(Bt[n][k], At[m][k], acc[ai][bj][m][n], 0, 0, 0); __builtin_amdgcn_s_setprio(0); } while (0)
; #define PG8_WAIT_V(n) asm volatile("s_waitcnt vmcnt(" #n ")" ::: "memory")
; #define PG8_WAIT_L(n) asm volatile("s_waitcnt lgkmcnt(" #n ")" ::: "memory")
; #define PG8_BAR __builtin_amdgcn_s_barrier()
; #define PG8_SCHED __builtin_amdgcn_sched_barrier(0)
; template <class Epi, class Ptrs>
; __device__ __forceinline__ void gemm_phase(LAS unsigned char* lds, const int K, const StaticOrder& S, const Ptrs& P, const Epi& E) {
;     ...
;             PG8_WAIT_V(6); PG8_BAR; PG8_MMA(1, 1, At, B1); PG8_BAR;
;             PG8_LDB(B0, 1, 0); PG8_SCHED; PG8_LDA(At, 1, 0); PG8_STAGE(PG8_SA(0, 1), a2 + hstep, voffA);
;             PG8_WAIT_L(8); PG8_BAR; PG8_WAIT_L(0); PG8_MMA(0, 0, At, B0); PG8_BAR; PG8_SCHED;
;             PG8_LDB(B1, 1, 1); PG8_STAGE(PG8_SB(1, 0), b3, voffB);
;             PG8_BAR; PG8_WAIT_L(0); PG8_MMA(0, 1, At, B1); PG8_BAR;
;             PG8_LDA(At, 1, 1); PG8_STAGE(PG8_SA(1, 0), a3, voffA);
;             PG8_BAR; PG8_WAIT_L(0); PG8_MMA(1, 0, At, B0); PG8_BAR; PG8_SCHED;
;             PG8_STAGE(PG8_SB(1, 1), b3 + hstep, voffB);
	v_mfma_f32_16x16x32_bf16 v[52:55], v[200:203], v[168:171], v[52:55]
	v_mfma_f32_16x16x32_bf16 v[52:55], v[204:207], v[172:175], v[52:55]
	v_mfma_f32_16x16x32_bf16 v[48:51], v[214:217], v[172:175], v[48:51]
	v_mfma_f32_16x16x32_bf16 v[48:51], v[210:213], v[168:171], v[48:51]
	v_mfma_f32_16x16x32_bf16 v[32:35], v[210:213], v[176:179], v[32:35]
	v_mfma_f32_16x16x32_bf16 v[32:35], v[214:217], v[180:183], v[32:35]
	v_mfma_f32_16x16x32_bf16 v[36:39], v[204:207], v[180:183], v[36:39]
	v_mfma_f32_16x16x32_bf16 v[36:39], v[200:203], v[176:179], v[36:39]
	v_mfma_f32_16x16x32_bf16 v[20:23], v[200:203], v[184:187], v[20:23]
	v_mfma_f32_16x16x32_bf16 v[20:23], v[204:207], v[188:191], v[20:23]
	v_mfma_f32_16x16x32_bf16 v[16:19], v[214:217], v[188:191], v[16:19]
	v_mfma_f32_16x16x32_bf16 v[16:19], v[210:213], v[184:187], v[16:19]
	v_mfma_f32_16x16x32_bf16 v[0:3], v[210:213], v[192:195], v[0:3]
	v_mfma_f32_16x16x32_bf16 v[0:3], v[214:217], v[196:199], v[0:3]
	v_mfma_f32_16x16x32_bf16 v[4:7], v[204:207], v[196:199], v[4:7]
	v_mfma_f32_16x16x32_bf16 v[4:7], v[200:203], v[192:195], v[4:7]
	s_barrier
	s_add_i32 s71, 0, 0x18000
	ds_read_b128 v[152:155], v252
	ds_read_b128 v[156:159], v252 offset:1024
	ds_read_b128 v[160:163], v252 offset:2048
	ds_read_b128 v[164:167], v252 offset:3072
	s_add_u32 s44, s44, 0x40000
	s_addc_u32 s45, s45, 0
	s_mov_b32 m0, s57
	ds_read_b128 v[168:171], v150 offset:32768
	ds_read_b128 v[172:175], v150 offset:33792
	ds_read_b128 v[176:179], v150 offset:34816
	ds_read_b128 v[180:183], v150 offset:35840
	ds_read_b128 v[184:187], v150 offset:36864
	ds_read_b128 v[188:191], v150 offset:37888
	ds_read_b128 v[192:195], v150 offset:38912
	ds_read_b128 v[196:199], v150 offset:39936
	global_load_lds_dwordx4 v128, s[44:45]
	s_mov_b32 m0, s58
	s_nop 0
	global_load_lds_dwordx4 v132, s[44:45]
	s_waitcnt lgkmcnt(8)
	s_barrier
	s_waitcnt lgkmcnt(0)
	v_mfma_f32_16x16x32_bf16 v[124:127], v[152:155], v[168:171], v[124:127]
	v_mfma_f32_16x16x32_bf16 v[124:127], v[156:159], v[172:175], v[124:127]
	v_mfma_f32_16x16x32_bf16 v[120:123], v[164:167], v[172:175], v[120:123]
	v_mfma_f32_16x16x32_bf16 v[120:123], v[160:163], v[168:171], v[120:123]
	v_mfma_f32_16x16x32_bf16 v[104:107], v[160:163], v[176:179], v[104:107]
	v_mfma_f32_16x16x32_bf16 v[104:107], v[164:167], v[180:183], v[104:107]
	v_mfma_f32_16x16x32_bf16 v[108:111], v[156:159], v[180:183], v[108:111]
	v_mfma_f32_16x16x32_bf16 v[108:111], v[152:155], v[176:179], v[108:111]
	v_mfma_f32_16x16x32_bf16 v[92:95], v[152:155], v[184:187], v[92:95]
	v_mfma_f32_16x16x32_bf16 v[92:95], v[156:159], v[188:191], v[92:95]
	v_mfma_f32_16x16x32_bf16 v[88:91], v[164:167], v[188:191], v[88:91]
	v_mfma_f32_16x16x32_bf16 v[88:91], v[160:163], v[184:187], v[88:91]
	v_mfma_f32_16x16x32_bf16 v[72:75], v[160:163], v[192:195], v[72:75]
	v_mfma_f32_16x16x32_bf16 v[72:75], v[164:167], v[196:199], v[72:75]
	v_mfma_f32_16x16x32_bf16 v[76:79], v[156:159], v[196:199], v[76:79]
	v_mfma_f32_16x16x32_bf16 v[76:79], v[152:155], v[192:195], v[76:79]
	s_barrier
	s_add_i32 s44, 0, 0x1c000
	s_add_i32 s45, s71, s51
	s_mov_b32 m0, s45
	ds_read_b128 v[200:203], v253
	ds_read_b128 v[204:207], v253 offset:1024
	ds_read_b128 v[210:213], v253 offset:2048
	ds_read_b128 v[214:217], v253 offset:3072
	global_load_lds_dwordx4 v130, s[76:77]
	s_add_i32 m0, s45, 0x2000
	s_nop 0
	global_load_lds_dwordx4 v134, s[76:77]
	s_barrier
	s_waitcnt lgkmcnt(0)
	v_mfma_f32_16x16x32_bf16 v[116:119], v[200:203], v[168:171], v[116:119]
	v_mfma_f32_16x16x32_bf16 v[116:119], v[204:207], v[172:175], v[116:119]
	v_mfma_f32_16x16x32_bf16 v[112:115], v[214:217], v[172:175], v[112:115]
	v_mfma_f32_16x16x32_bf16 v[112:115], v[210:213], v[168:171], v[112:115]
	v_mfma_f32_16x16x32_bf16 v[96:99], v[210:213], v[176:179], v[96:99]
	v_mfma_f32_16x16x32_bf16 v[96:99], v[214:217], v[180:183], v[96:99]
	v_mfma_f32_16x16x32_bf16 v[100:103], v[204:207], v[180:183], v[100:103]
	v_mfma_f32_16x16x32_bf16 v[100:103], v[200:203], v[176:179], v[100:103]
	v_mfma_f32_16x16x32_bf16 v[84:87], v[200:203], v[184:187], v[84:87]
	v_mfma_f32_16x16x32_bf16 v[84:87], v[204:207], v[188:191], v[84:87]
	v_mfma_f32_16x16x32_bf16 v[80:83], v[214:217], v[188:191], v[80:83]
	v_mfma_f32_16x16x32_bf16 v[80:83], v[210:213], v[184:187], v[80:83]
	v_mfma_f32_16x16x32_bf16 v[64:67], v[210:213], v[192:195], v[64:67]
	v_mfma_f32_16x16x32_bf16 v[64:67], v[214:217], v[196:199], v[64:67]
	v_mfma_f32_16x16x32_bf16 v[68:71], v[204:207], v[196:199], v[68:71]
	v_mfma_f32_16x16x32_bf16 v[68:71], v[200:203], v[192:195], v[68:71]
	s_barrier
	s_mov_b32 m0, s61
	ds_read_b128 v[168:171], v150 offset:49152
	ds_read_b128 v[172:175], v150 offset:50176
	ds_read_b128 v[176:179], v150 offset:51200
	ds_read_b128 v[180:183], v150 offset:52224
	ds_read_b128 v[184:187], v150 offset:53248
	ds_read_b128 v[188:191], v150 offset:54272
	ds_read_b128 v[192:195], v150 offset:55296
	ds_read_b128 v[196:199], v150 offset:56320
	global_load_lds_dwordx4 v128, s[78:79]
	s_mov_b32 m0, s62
	s_nop 0
	global_load_lds_dwordx4 v132, s[78:79]
	s_barrier
	s_waitcnt lgkmcnt(0)
	v_mfma_f32_16x16x32_bf16 v[60:63], v[152:155], v[168:171], v[60:63]
	v_mfma_f32_16x16x32_bf16 v[60:63], v[156:159], v[172:175], v[60:63]
	v_mfma_f32_16x16x32_bf16 v[56:59], v[164:167], v[172:175], v[56:59]
	v_mfma_f32_16x16x32_bf16 v[56:59], v[160:163], v[168:171], v[56:59]
	v_mfma_f32_16x16x32_bf16 v[40:43], v[160:163], v[176:179], v[40:43]
	v_mfma_f32_16x16x32_bf16 v[40:43], v[164:167], v[180:183], v[40:43]
	v_mfma_f32_16x16x32_bf16 v[44:47], v[156:159], v[180:183], v[44:47]
	v_mfma_f32_16x16x32_bf16 v[44:47], v[152:155], v[176:179], v[44:47]
	v_mfma_f32_16x16x32_bf16 v[28:31], v[152:155], v[184:187], v[28:31]
	v_mfma_f32_16x16x32_bf16 v[28:31], v[156:159], v[188:191], v[28:31]
	v_mfma_f32_16x16x32_bf16 v[24:27], v[164:167], v[188:191], v[24:27]
	v_mfma_f32_16x16x32_bf16 v[24:27], v[160:163], v[184:187], v[24:27]
	v_mfma_f32_16x16x32_bf16 v[8:11], v[160:163], v[192:195], v[8:11]
	v_mfma_f32_16x16x32_bf16 v[8:11], v[164:167], v[196:199], v[8:11]
	v_mfma_f32_16x16x32_bf16 v[12:15], v[156:159], v[196:199], v[12:15]
	v_mfma_f32_16x16x32_bf16 v[12:15], v[152:155], v[192:195], v[12:15]
	s_barrier
; __device__ __forceinline__ unsigned cvt_pk_bf16(float lo, float hi) { unsigned r; asm volatile("v_cvt_pk_bf16_f32 %0, %1, %2" : "=v"(r) : "v"(lo), "v"(hi)); return r; }
; #define PG8_STAGE(bufoff, gbase, voff) do { _Pragma("unroll") for (int _i = 0; _i < 2; ++_i) \
;         __builtin_amdgcn_global_load_lds((const unsigned*)((const char*)(gbase) + (voff)[_i]), (LAS unsigned*)(lds + (bufoff) + ldsw + _i * 8192), 16, 0, 0); } while (0)
; #define PG8_MMA(ai, bj, At, Bt) do { __builtin_amdgcn_s_setprio(1); _Pragma("unroll") for (int m = 0; m < 4; ++m) _Pragma("unroll") for (int n = 0; n < 2; ++n) _Pragma("unroll") for (int k = 0; k < 2; ++k) \
;         acc[ai][bj][m][n] = __builtin_amdgcn_mfma_f32_16x16x32_bf16(Bt[n][k], At[m][k], acc[ai][bj][m][n], 0, 0, 0); __builtin_amdgcn_s_setprio(0); } while (0)
; #define PG8_WAIT_V(n) asm volatile("s_waitcnt vmcnt(" #n ")" ::: "memory")
; #define PG8_BAR __builtin_amdgcn_s_barrier()
; template <class Epi, class Ptrs>
; __device__ __forceinline__ void gemm_phase(LAS unsigned char* lds, const int K, const StaticOrder& S, const Ptrs& P, const Epi& E) {
;     ...
;             PG8_STAGE(PG8_SB(1, 1), b3 + hstep, voffB);
;             PG8_WAIT_V(6); PG8_BAR; PG8_MMA(1, 1, At, B1); PG8_BAR;
;     __device__ __forceinline__ void operator()(const f32x4 (&acc)[2][2][4][2], const Unit& u, int ui, int wr, int wc, int fr, int fq) const {
;         const int row0 = u.pm * 256 + wr * 64 + fr, col0 = u.pn * 256 + wc * 32 + 8 * fq;
; #pragma unroll
;         for (int ai = 0; ai < 2; ++ai)
; #pragma unroll
;             for (int m = 0; m < 4; ++m) { bf16_t* rowp = hid + (size_t)(row0 + ai * 128 + m * 16) * DFF + col0;
; #pragma unroll
;                 for (int bj = 0; bj < 2; ++bj) { f32x4 v0 = acc[ai][bj][m][0], v1 = acc[ai][bj][m][1];
; #pragma unroll
;                     for (int j = 0; j < 4; ++j) { const float a = fmaxf(v0[j], 0.f), b = fmaxf(v1[j], 0.f); v0[j] = a * a; v1[j] = b * b; }
;                     u32x4 w; w.x = cvt_pk_bf16(v0[0], v0[1]); w.y = cvt_pk_bf16(v0[2], v0[3]); w.z = cvt_pk_bf16(v1[0], v1[1]); w.w = cvt_pk_bf16(v1[2], v1[3]);
;                     *(u32x4*)(rowp + bj * 128) = w; } }
	s_add_u32 s42, s42, 0x40080
	s_addc_u32 s43, s43, 0
	s_add_i32 s44, s44, s51
	s_mov_b32 m0, s44
	s_nop 0
	global_load_lds_dwordx4 v130, s[42:43]
	s_add_i32 m0, s44, 0x2000
	s_nop 0
	global_load_lds_dwordx4 v134, s[42:43]
	s_waitcnt vmcnt(6)
	s_barrier
	v_mfma_f32_16x16x32_bf16 v[52:55], v[200:203], v[168:171], v[52:55]
	v_mfma_f32_16x16x32_bf16 v[52:55], v[204:207], v[172:175], v[52:55]
	v_mfma_f32_16x16x32_bf16 v[48:51], v[214:217], v[172:175], v[48:51]
	v_mfma_f32_16x16x32_bf16 v[48:51], v[210:213], v[168:171], v[48:51]
	v_mfma_f32_16x16x32_bf16 v[32:35], v[210:213], v[176:179], v[32:35]
	v_mfma_f32_16x16x32_bf16 v[32:35], v[214:217], v[180:183], v[32:35]
	v_mfma_f32_16x16x32_bf16 v[36:39], v[204:207], v[180:183], v[36:39]
	v_mfma_f32_16x16x32_bf16 v[36:39], v[200:203], v[176:179], v[36:39]
	v_mfma_f32_16x16x32_bf16 v[20:23], v[200:203], v[184:187], v[20:23]
	v_mfma_f32_16x16x32_bf16 v[20:23], v[204:207], v[188:191], v[20:23]
	v_mfma_f32_16x16x32_bf16 v[16:19], v[214:217], v[188:191], v[16:19]
	v_mfma_f32_16x16x32_bf16 v[16:19], v[210:213], v[184:187], v[16:19]
	v_mfma_f32_16x16x32_bf16 v[0:3], v[210:213], v[192:195], v[0:3]
	v_mfma_f32_16x16x32_bf16 v[0:3], v[214:217], v[196:199], v[0:3]
	v_mfma_f32_16x16x32_bf16 v[4:7], v[204:207], v[196:199], v[4:7]
	v_mfma_f32_16x16x32_bf16 v[4:7], v[200:203], v[192:195], v[4:7]
	s_barrier
	s_add_i32 s70, s70, 2
	s_add_u32 s40, s40, 0x100
	s_addc_u32 s41, s41, 0
	s_add_u32 s23, s23, 0x100
	s_addc_u32 s25, s25, 0
	s_cmp_gt_u32 s70, 13
	s_cbranch_scc0 .LBB0_433
	v_lshl_add_u32 v152, s38, 8, v146
	v_lshl_or_b32 v144, s69, 8, v148
	v_lshlrev_b32_e32 v152, 13, v152
	v_lshl_add_u32 v144, v144, 1, v152
	v_add_u32_e32 v145, 0x20000, v144
	v_add_u32_e32 v152, 0x40000, v144
	v_add_u32_e32 v153, 0x60000, v144
	v_add_u32_e32 v154, 0x100000, v144
	v_add_u32_e32 v155, 0x120000, v144
	v_add_u32_e32 v156, 0x140000, v144
	v_add_u32_e32 v157, 0x160000, v144
	s_and_b64 vcc, exec, s[4:5]
	s_mov_b32 s69, s22
	s_mov_b32 s38, s24
	s_mov_b64 s[40:41], s[0:1]
	s_mov_b64 s[42:43], s[36:37]
	v_max_f32_e32 v120, 0, v120
	v_max_f32_e32 v121, 0, v121
	v_max_f32_e32 v122, 0, v122
	v_max_f32_e32 v123, 0, v123
	v_max_f32_e32 v124, 0, v124
	v_max_f32_e32 v125, 0, v125
	v_max_f32_e32 v126, 0, v126
	v_max_f32_e32 v127, 0, v127
	v_mul_f32_e32 v120, v120, v120
	v_mul_f32_e32 v121, v121, v121
	v_mul_f32_e32 v122, v122, v122
	v_mul_f32_e32 v123, v123, v123
	v_mul_f32_e32 v124, v124, v124
	v_mul_f32_e32 v125, v125, v125
	v_mul_f32_e32 v126, v126, v126
	v_mul_f32_e32 v127, v127, v127
	v_cvt_pk_bf16_f32 v124, v124, v125
	v_cvt_pk_bf16_f32 v125, v126, v127
	v_cvt_pk_bf16_f32 v126, v120, v121
	v_cvt_pk_bf16_f32 v127, v122, v123
	global_store_dwordx4 v144, v[124:127], s[10:11]
	v_max_f32_e32 v112, 0, v112
	v_max_f32_e32 v113, 0, v113
	v_max_f32_e32 v114, 0, v114
	v_max_f32_e32 v115, 0, v115
	v_max_f32_e32 v116, 0, v116
	v_max_f32_e32 v117, 0, v117
	v_max_f32_e32 v118, 0, v118
	v_max_f32_e32 v119, 0, v119
	v_mul_f32_e32 v112, v112, v112
	v_mul_f32_e32 v113, v113, v113
	v_mul_f32_e32 v114, v114, v114
	v_mul_f32_e32 v115, v115, v115
	v_mul_f32_e32 v116, v116, v116
	v_mul_f32_e32 v117, v117, v117
	v_mul_f32_e32 v118, v118, v118
	v_mul_f32_e32 v119, v119, v119
	v_cvt_pk_bf16_f32 v116, v116, v117
	v_cvt_pk_bf16_f32 v117, v118, v119
	v_cvt_pk_bf16_f32 v118, v112, v113
	v_cvt_pk_bf16_f32 v119, v114, v115
	global_store_dwordx4 v144, v[116:119], s[10:11] offset:256
	v_max_f32_e32 v104, 0, v104
	v_max_f32_e32 v105, 0, v105
	v_max_f32_e32 v106, 0, v106
	v_max_f32_e32 v107, 0, v107
	v_max_f32_e32 v108, 0, v108
	v_max_f32_e32 v109, 0, v109
	v_max_f32_e32 v110, 0, v110
	v_max_f32_e32 v111, 0, v111
	v_mul_f32_e32 v104, v104, v104
	v_mul_f32_e32 v105, v105, v105
	v_mul_f32_e32 v106, v106, v106
	v_mul_f32_e32 v107, v107, v107
	v_mul_f32_e32 v108, v108, v108
	v_mul_f32_e32 v109, v109, v109
	v_mul_f32_e32 v110, v110, v110
	v_mul_f32_e32 v111, v111, v111
	v_cvt_pk_bf16_f32 v108, v108, v109
	v_cvt_pk_bf16_f32 v109, v110, v111
	v_cvt_pk_bf16_f32 v110, v104, v105
	v_cvt_pk_bf16_f32 v111, v106, v107
	global_store_dwordx4 v145, v[108:111], s[10:11]
	v_max_f32_e32 v96, 0, v96
	v_max_f32_e32 v97, 0, v97
	v_max_f32_e32 v98, 0, v98
	v_max_f32_e32 v99, 0, v99
	v_max_f32_e32 v100, 0, v100
	v_max_f32_e32 v101, 0, v101
	v_max_f32_e32 v102, 0, v102
	v_max_f32_e32 v103, 0, v103
	v_mul_f32_e32 v96, v96, v96
	v_mul_f32_e32 v97, v97, v97
	v_mul_f32_e32 v98, v98, v98
	v_mul_f32_e32 v99, v99, v99
	v_mul_f32_e32 v100, v100, v100
	v_mul_f32_e32 v101, v101, v101
	v_mul_f32_e32 v102, v102, v102
	v_mul_f32_e32 v103, v103, v103
	v_cvt_pk_bf16_f32 v100, v100, v101
	v_cvt_pk_bf16_f32 v101, v102, v103
	v_cvt_pk_bf16_f32 v102, v96, v97
	v_cvt_pk_bf16_f32 v103, v98, v99
	global_store_dwordx4 v145, v[100:103], s[10:11] offset:256
	v_max_f32_e32 v88, 0, v88
	v_max_f32_e32 v89, 0, v89
	v_max_f32_e32 v90, 0, v90
	v_max_f32_e32 v91, 0, v91
	v_max_f32_e32 v92, 0, v92
	v_max_f32_e32 v93, 0, v93
	v_max_f32_e32 v94, 0, v94
	v_max_f32_e32 v95, 0, v95
	v_mul_f32_e32 v88, v88, v88
	v_mul_f32_e32 v89, v89, v89
	v_mul_f32_e32 v90, v90, v90
	v_mul_f32_e32 v91, v91, v91
	v_mul_f32_e32 v92, v92, v92
	v_mul_f32_e32 v93, v93, v93
	v_mul_f32_e32 v94, v94, v94
	v_mul_f32_e32 v95, v95, v95
	v_cvt_pk_bf16_f32 v92, v92, v93
	v_cvt_pk_bf16_f32 v93, v94, v95
	v_cvt_pk_bf16_f32 v94, v88, v89
	v_cvt_pk_bf16_f32 v95, v90, v91
	global_store_dwordx4 v152, v[92:95], s[10:11]
	v_max_f32_e32 v80, 0, v80
	v_max_f32_e32 v81, 0, v81
	v_max_f32_e32 v82, 0, v82
	v_max_f32_e32 v83, 0, v83
	v_max_f32_e32 v84, 0, v84
	v_max_f32_e32 v85, 0, v85
	v_max_f32_e32 v86, 0, v86
	v_max_f32_e32 v87, 0, v87
	v_mul_f32_e32 v80, v80, v80
; __device__ __forceinline__ unsigned cvt_pk_bf16(float lo, float hi) { unsigned r; asm volatile("v_cvt_pk_bf16_f32 %0, %1, %2" : "=v"(r) : "v"(lo), "v"(hi)); return r; }
;     __device__ __forceinline__ void operator()(const f32x4 (&acc)[2][2][4][2], const Unit& u, int ui, int wr, int wc, int fr, int fq) const {
;     ...
;             for (int m = 0; m < 4; ++m) { bf16_t* rowp = hid + (size_t)(row0 + ai * 128 + m * 16) * DFF + col0;
; #pragma unroll
;                 for (int bj = 0; bj < 2; ++bj) { f32x4 v0 = acc[ai][bj][m][0], v1 = acc[ai][bj][m][1];
; #pragma unroll
;                     for (int j = 0; j < 4; ++j) { const float a = fmaxf(v0[j], 0.f), b = fmaxf(v1[j], 0.f); v0[j] = a * a; v1[j] = b * b; }
;                     u32x4 w; w.x = cvt_pk_bf16(v0[0], v0[1]); w.y = cvt_pk_bf16(v0[2], v0[3]); w.z = cvt_pk_bf16(v1[0], v1[1]); w.w = cvt_pk_bf16(v1[2], v1[3]);
;                     *(u32x4*)(rowp + bj * 128) = w; } }
	v_mul_f32_e32 v81, v81, v81
	v_mul_f32_e32 v82, v82, v82
	v_mul_f32_e32 v83, v83, v83
	v_mul_f32_e32 v84, v84, v84
	v_mul_f32_e32 v85, v85, v85
	v_mul_f32_e32 v86, v86, v86
	v_mul_f32_e32 v87, v87, v87
	v_cvt_pk_bf16_f32 v84, v84, v85
	v_cvt_pk_bf16_f32 v85, v86, v87
	v_cvt_pk_bf16_f32 v86, v80, v81
	v_cvt_pk_bf16_f32 v87, v82, v83
	global_store_dwordx4 v152, v[84:87], s[10:11] offset:256
	v_max_f32_e32 v72, 0, v72
	v_max_f32_e32 v73, 0, v73
	v_max_f32_e32 v74, 0, v74
	v_max_f32_e32 v75, 0, v75
	v_max_f32_e32 v76, 0, v76
	v_max_f32_e32 v77, 0, v77
	v_max_f32_e32 v78, 0, v78
	v_max_f32_e32 v79, 0, v79
	v_mul_f32_e32 v72, v72, v72
	v_mul_f32_e32 v73, v73, v73
	v_mul_f32_e32 v74, v74, v74
	v_mul_f32_e32 v75, v75, v75
	v_mul_f32_e32 v76, v76, v76
	v_mul_f32_e32 v77, v77, v77
	v_mul_f32_e32 v78, v78, v78
	v_mul_f32_e32 v79, v79, v79
	v_cvt_pk_bf16_f32 v76, v76, v77
	v_cvt_pk_bf16_f32 v77, v78, v79
	v_cvt_pk_bf16_f32 v78, v72, v73
	v_cvt_pk_bf16_f32 v79, v74, v75
	global_store_dwordx4 v153, v[76:79], s[10:11]
	v_max_f32_e32 v64, 0, v64
	v_max_f32_e32 v65, 0, v65
	v_max_f32_e32 v66, 0, v66
	v_max_f32_e32 v67, 0, v67
	v_max_f32_e32 v68, 0, v68
	v_max_f32_e32 v69, 0, v69
	v_max_f32_e32 v70, 0, v70
	v_max_f32_e32 v71, 0, v71
	v_mul_f32_e32 v64, v64, v64
	v_mul_f32_e32 v65, v65, v65
	v_mul_f32_e32 v66, v66, v66
	v_mul_f32_e32 v67, v67, v67
	v_mul_f32_e32 v68, v68, v68
	v_mul_f32_e32 v69, v69, v69
	v_mul_f32_e32 v70, v70, v70
	v_mul_f32_e32 v71, v71, v71
	v_cvt_pk_bf16_f32 v68, v68, v69
	v_cvt_pk_bf16_f32 v69, v70, v71
	v_cvt_pk_bf16_f32 v70, v64, v65
	v_cvt_pk_bf16_f32 v71, v66, v67
	global_store_dwordx4 v153, v[68:71], s[10:11] offset:256
	v_max_f32_e32 v56, 0, v56
	v_max_f32_e32 v57, 0, v57
	v_max_f32_e32 v58, 0, v58
	v_max_f32_e32 v59, 0, v59
	v_max_f32_e32 v60, 0, v60
	v_max_f32_e32 v61, 0, v61
	v_max_f32_e32 v62, 0, v62
	v_max_f32_e32 v63, 0, v63
	v_mul_f32_e32 v56, v56, v56
	v_mul_f32_e32 v57, v57, v57
	v_mul_f32_e32 v58, v58, v58
	v_mul_f32_e32 v59, v59, v59
	v_mul_f32_e32 v60, v60, v60
	v_mul_f32_e32 v61, v61, v61
	v_mul_f32_e32 v62, v62, v62
	v_mul_f32_e32 v63, v63, v63
	v_cvt_pk_bf16_f32 v60, v60, v61
	v_cvt_pk_bf16_f32 v61, v62, v63
	v_cvt_pk_bf16_f32 v62, v56, v57
	v_cvt_pk_bf16_f32 v63, v58, v59
	global_store_dwordx4 v154, v[60:63], s[10:11]
	v_max_f32_e32 v48, 0, v48
	v_max_f32_e32 v49, 0, v49
	v_max_f32_e32 v50, 0, v50
	v_max_f32_e32 v51, 0, v51
	v_max_f32_e32 v52, 0, v52
	v_max_f32_e32 v53, 0, v53
	v_max_f32_e32 v54, 0, v54
	v_max_f32_e32 v55, 0, v55
	v_mul_f32_e32 v48, v48, v48
	v_mul_f32_e32 v49, v49, v49
	v_mul_f32_e32 v50, v50, v50
	v_mul_f32_e32 v51, v51, v51
	v_mul_f32_e32 v52, v52, v52
	v_mul_f32_e32 v53, v53, v53
	v_mul_f32_e32 v54, v54, v54
	v_mul_f32_e32 v55, v55, v55
	v_cvt_pk_bf16_f32 v52, v52, v53
	v_cvt_pk_bf16_f32 v53, v54, v55
	v_cvt_pk_bf16_f32 v54, v48, v49
	v_cvt_pk_bf16_f32 v55, v50, v51
	global_store_dwordx4 v154, v[52:55], s[10:11] offset:256
	v_max_f32_e32 v40, 0, v40
	v_max_f32_e32 v41, 0, v41
	v_max_f32_e32 v42, 0, v42
	v_max_f32_e32 v43, 0, v43
	v_max_f32_e32 v44, 0, v44
	v_max_f32_e32 v45, 0, v45
	v_max_f32_e32 v46, 0, v46
	v_max_f32_e32 v47, 0, v47
	v_mul_f32_e32 v40, v40, v40
	v_mul_f32_e32 v41, v41, v41
	v_mul_f32_e32 v42, v42, v42
	v_mul_f32_e32 v43, v43, v43
	v_mul_f32_e32 v44, v44, v44
	v_mul_f32_e32 v45, v45, v45
	v_mul_f32_e32 v46, v46, v46
	v_mul_f32_e32 v47, v47, v47
	v_cvt_pk_bf16_f32 v44, v44, v45
	v_cvt_pk_bf16_f32 v45, v46, v47
	v_cvt_pk_bf16_f32 v46, v40, v41
	v_cvt_pk_bf16_f32 v47, v42, v43
	global_store_dwordx4 v155, v[44:47], s[10:11]
	v_max_f32_e32 v32, 0, v32
	v_max_f32_e32 v33, 0, v33
	v_max_f32_e32 v34, 0, v34
	v_max_f32_e32 v35, 0, v35
	v_max_f32_e32 v36, 0, v36
	v_max_f32_e32 v37, 0, v37
	v_max_f32_e32 v38, 0, v38
	v_max_f32_e32 v39, 0, v39
	v_mul_f32_e32 v32, v32, v32
	v_mul_f32_e32 v33, v33, v33
	v_mul_f32_e32 v34, v34, v34
	v_mul_f32_e32 v35, v35, v35
	v_mul_f32_e32 v36, v36, v36
	v_mul_f32_e32 v37, v37, v37
	v_mul_f32_e32 v38, v38, v38
	v_mul_f32_e32 v39, v39, v39
	v_cvt_pk_bf16_f32 v36, v36, v37
	v_cvt_pk_bf16_f32 v37, v38, v39
	v_cvt_pk_bf16_f32 v38, v32, v33
	v_cvt_pk_bf16_f32 v39, v34, v35
	global_store_dwordx4 v155, v[36:39], s[10:11] offset:256
	v_max_f32_e32 v24, 0, v24
	v_max_f32_e32 v25, 0, v25
	v_max_f32_e32 v26, 0, v26
	v_max_f32_e32 v27, 0, v27
	v_max_f32_e32 v28, 0, v28
	v_max_f32_e32 v29, 0, v29
	v_max_f32_e32 v30, 0, v30
	v_max_f32_e32 v31, 0, v31
	v_mul_f32_e32 v24, v24, v24
	v_mul_f32_e32 v25, v25, v25
	v_mul_f32_e32 v26, v26, v26
	v_mul_f32_e32 v27, v27, v27
	v_mul_f32_e32 v28, v28, v28
	v_mul_f32_e32 v29, v29, v29
	v_mul_f32_e32 v30, v30, v30
	v_mul_f32_e32 v31, v31, v31
	v_cvt_pk_bf16_f32 v28, v28, v29
	v_cvt_pk_bf16_f32 v29, v30, v31
	v_cvt_pk_bf16_f32 v30, v24, v25
	v_cvt_pk_bf16_f32 v31, v26, v27
	global_store_dwordx4 v156, v[28:31], s[10:11]
	v_max_f32_e32 v16, 0, v16
	v_max_f32_e32 v17, 0, v17
	v_max_f32_e32 v18, 0, v18
	v_max_f32_e32 v19, 0, v19
	v_max_f32_e32 v20, 0, v20
	v_max_f32_e32 v21, 0, v21
	v_max_f32_e32 v22, 0, v22
	v_max_f32_e32 v23, 0, v23
	v_mul_f32_e32 v16, v16, v16
	v_mul_f32_e32 v17, v17, v17
	v_mul_f32_e32 v18, v18, v18
	v_mul_f32_e32 v19, v19, v19
	v_mul_f32_e32 v20, v20, v20
	v_mul_f32_e32 v21, v21, v21
	v_mul_f32_e32 v22, v22, v22
	v_mul_f32_e32 v23, v23, v23
	v_cvt_pk_bf16_f32 v20, v20, v21
	v_cvt_pk_bf16_f32 v21, v22, v23
	v_cvt_pk_bf16_f32 v22, v16, v17
	v_cvt_pk_bf16_f32 v23, v18, v19
	global_store_dwordx4 v156, v[20:23], s[10:11] offset:256
	v_max_f32_e32 v8, 0, v8
	v_max_f32_e32 v9, 0, v9
	v_max_f32_e32 v10, 0, v10
	v_max_f32_e32 v11, 0, v11
	v_max_f32_e32 v12, 0, v12
	v_max_f32_e32 v13, 0, v13
	v_max_f32_e32 v14, 0, v14
	v_max_f32_e32 v15, 0, v15
	v_mul_f32_e32 v8, v8, v8
	v_mul_f32_e32 v9, v9, v9
	v_mul_f32_e32 v10, v10, v10
	v_mul_f32_e32 v11, v11, v11
	v_mul_f32_e32 v12, v12, v12
	v_mul_f32_e32 v13, v13, v13
	v_mul_f32_e32 v14, v14, v14
	v_mul_f32_e32 v15, v15, v15
	v_cvt_pk_bf16_f32 v12, v12, v13
	v_cvt_pk_bf16_f32 v13, v14, v15
	v_cvt_pk_bf16_f32 v14, v8, v9
	v_cvt_pk_bf16_f32 v15, v10, v11
	global_store_dwordx4 v157, v[12:15], s[10:11]
	v_max_f32_e32 v0, 0, v0
	v_max_f32_e32 v1, 0, v1
	v_max_f32_e32 v2, 0, v2
	v_max_f32_e32 v3, 0, v3
	v_max_f32_e32 v4, 0, v4
	v_max_f32_e32 v5, 0, v5
	v_max_f32_e32 v6, 0, v6
	v_max_f32_e32 v7, 0, v7
	v_mul_f32_e32 v0, v0, v0
	v_mul_f32_e32 v1, v1, v1
	v_mul_f32_e32 v2, v2, v2
	v_mul_f32_e32 v3, v3, v3
	v_mul_f32_e32 v4, v4, v4
	v_mul_f32_e32 v5, v5, v5
	v_mul_f32_e32 v6, v6, v6
	v_mul_f32_e32 v7, v7, v7
	v_cvt_pk_bf16_f32 v4, v4, v5
	v_cvt_pk_bf16_f32 v5, v6, v7
	v_cvt_pk_bf16_f32 v6, v0, v1
	v_cvt_pk_bf16_f32 v7, v2, v3
	global_store_dwordx4 v157, v[4:7], s[10:11] offset:256
	s_cbranch_vccz .LBB0_428
	s_waitcnt vmcnt(0)
	s_setprio 0
	s_cmpk_gt_u32 s46, 0xff
	s_cbranch_scc1 .LBB0_437
	s_barrier
